# v047 with the P6 split-K consumer reading the partial sums with plain (L2-cached) loads instead of sc1 loads
# baseline (speedup 1.0000x reference)
; #define REPS(k) for (int rep_ = 0; rep_ < (((RPM) >> (k)) & 1) + 1; ++rep_)
; __global__ void __launch_bounds__(512, 2) hybrid_fwd(Params p) {
;     ...
;         if (PH(6)) REPS(6) { PHB
;             SchedQH S{ws, l, G, c};
;             EpiB E;
;             pg8::gemm_phase<EpiB, SchedQH, false, true>(lds, tid, D_, S, E);
.Lp6_wait_done:
	s_or_b64 exec, exec, s[22:23]
	s_waitcnt vmcnt(0) lgkmcnt(0)
	s_barrier
	s_lshl_b32 s18, s24, 17
	s_lshl_b32 s19, s25, 8
	s_and_b32 s19, s19, 0x1c000
	s_add_i32 s18, s18, s19
	s_add_u32 s20, s50, 0x27600000
	s_addc_u32 s21, s51, 0
	s_add_u32 s20, s20, s18
	s_addc_u32 s21, s21, 0
	v_and_b32_e32 v96, 63, v147
	v_lshlrev_b32_e32 v96, 4, v96
	v_mov_b32_e32 v97, 0
	s_mov_b64 s[22:23], 0x1000
	v_lshl_add_u64 v[96:97], s[20:21], 0, v[96:97]
	global_load_dwordx4 v[102:105], v[96:97], off
	global_load_dwordx4 v[106:109], v[96:97], off offset:1024
	global_load_dwordx4 v[110:113], v[96:97], off offset:2048
	global_load_dwordx4 v[114:117], v[96:97], off offset:3072
	v_lshl_add_u64 v[96:97], v[96:97], 0, s[22:23]
	global_load_dwordx4 v[118:121], v[96:97], off
	global_load_dwordx4 v[122:125], v[96:97], off offset:1024
	global_load_dwordx4 v[126:129], v[96:97], off offset:2048
	global_load_dwordx4 v[130:133], v[96:97], off offset:3072
	v_lshl_add_u64 v[96:97], v[96:97], 0, s[22:23]
	global_load_dwordx4 v[148:151], v[96:97], off
	global_load_dwordx4 v[152:155], v[96:97], off offset:1024
	global_load_dwordx4 v[156:159], v[96:97], off offset:2048
	global_load_dwordx4 v[160:163], v[96:97], off offset:3072
	v_lshl_add_u64 v[96:97], v[96:97], 0, s[22:23]
	global_load_dwordx4 v[164:167], v[96:97], off
	global_load_dwordx4 v[168:171], v[96:97], off offset:1024
	global_load_dwordx4 v[172:175], v[96:97], off offset:2048
	global_load_dwordx4 v[176:179], v[96:97], off offset:3072
	s_waitcnt vmcnt(0)
	v_add_f32_e32 v0, v0, v102
	v_add_f32_e32 v1, v1, v103
	v_add_f32_e32 v2, v2, v104
	v_add_f32_e32 v3, v3, v105
	v_add_f32_e32 v4, v4, v106
	v_add_f32_e32 v5, v5, v107
	v_add_f32_e32 v6, v6, v108
	v_add_f32_e32 v7, v7, v109
	v_add_f32_e32 v8, v8, v110
	v_add_f32_e32 v9, v9, v111
	v_add_f32_e32 v10, v10, v112
	v_add_f32_e32 v11, v11, v113
	v_add_f32_e32 v12, v12, v114
	v_add_f32_e32 v13, v13, v115
	v_add_f32_e32 v14, v14, v116
	v_add_f32_e32 v15, v15, v117
	v_add_f32_e32 v16, v16, v118
	v_add_f32_e32 v17, v17, v119
	v_add_f32_e32 v18, v18, v120
	v_add_f32_e32 v19, v19, v121
	v_add_f32_e32 v20, v20, v122
	v_add_f32_e32 v21, v21, v123
	v_add_f32_e32 v22, v22, v124
	v_add_f32_e32 v23, v23, v125
	v_add_f32_e32 v24, v24, v126
	v_add_f32_e32 v25, v25, v127
	v_add_f32_e32 v26, v26, v128
	v_add_f32_e32 v27, v27, v129
	v_add_f32_e32 v28, v28, v130
	v_add_f32_e32 v29, v29, v131
	v_add_f32_e32 v30, v30, v132
	v_add_f32_e32 v31, v31, v133
	v_add_f32_e32 v32, v32, v148
	v_add_f32_e32 v33, v33, v149
	v_add_f32_e32 v34, v34, v150
	v_add_f32_e32 v35, v35, v151
	v_add_f32_e32 v36, v36, v152
	v_add_f32_e32 v37, v37, v153
	v_add_f32_e32 v38, v38, v154
	v_add_f32_e32 v39, v39, v155
	v_add_f32_e32 v40, v40, v156
	v_add_f32_e32 v41, v41, v157
	v_add_f32_e32 v42, v42, v158
	v_add_f32_e32 v43, v43, v159
	v_add_f32_e32 v44, v44, v160
	v_add_f32_e32 v45, v45, v161
	v_add_f32_e32 v46, v46, v162
	v_add_f32_e32 v47, v47, v163
	v_add_f32_e32 v48, v48, v164
	v_add_f32_e32 v49, v49, v165
	v_add_f32_e32 v50, v50, v166
	v_add_f32_e32 v51, v51, v167
	v_add_f32_e32 v52, v52, v168
	v_add_f32_e32 v53, v53, v169
	v_add_f32_e32 v54, v54, v170
	v_add_f32_e32 v55, v55, v171
	v_add_f32_e32 v56, v56, v172
	v_add_f32_e32 v57, v57, v173
	v_add_f32_e32 v58, v58, v174
	v_add_f32_e32 v59, v59, v175
	v_add_f32_e32 v60, v60, v176
	v_add_f32_e32 v61, v61, v177
	v_add_f32_e32 v62, v62, v178
	v_add_f32_e32 v63, v63, v179
